# MLA loop: waves 4-7 do next-tile LDS store + prefetch after their QK MFMAs (role split between SIMD partner waves)
# baseline (speedup 1.0000x reference)
; __global__ void __launch_bounds__(512, 2) mega_fwd(Params P) {
;   __shared__ __attribute__((aligned(16))) unsigned char smem[LDS_BYTES];
;   __shared__ uint4 xb_words;
;   cg::grid_group grid = cg::this_grid();
;   if (P.ws == nullptr) grid.sync();
;   if (threadIdx.x == 0) xb_words = make_uint4(0u, 0u, 0u, 0u);
;   __syncthreads();
_Z8mega_fwd6Params:
	v_readfirstlane_b32 s101, v0
	s_nop 3
	s_bfe_u32 s101, s101, 0x10008
	s_load_dwordx4 s[72:75], s[0:1], 0xc0
	s_add_u32 s4, s0, 0xc8
	s_addc_u32 s5, s1, 0
	s_mov_b32 s70, s2
	s_mov_b64 s[2:3], 0
	s_waitcnt lgkmcnt(0)
	s_cmp_eq_u64 s[72:73], 0
	s_cbranch_scc1 .LBB0_2
	v_and_b32_e32 v192, 0x3ff, v0
	s_branch .LBB0_3

; DI void kv96x8_fetch(KVR8& R, const bf16_t* knbase, const bf16_t* krbase, const bf16_t* vtbase, int key0, int tid) {
;   const int row = tid >> 3, kc = tid & 7, rr = (tid & 255) >> 2, rc = tid & 3;
;   R.k0 = ldg16(knbase + (size_t)(key0 + row) * 1024 + kc * 8);
;   R.k2 = ldg16(krbase + (size_t)(key0 + rr) * 32 + rc * 8);
;   R.v0 = ldg16(vtbase + (size_t)row * SEQ + key0 + kc * 8);
; }
; DI void kv96x8_store(const KVR8& R, bf16_t* sK, bf16_t* sVt, int tid) {
;   const int row = tid >> 3, kc = tid & 7, rr = (tid & 255) >> 2, rc = tid & 3;
;   *(u32x4*)(sK + row * 104 + kc * 8) = R.k0;
;   if (tid < 256) *(u32x4*)(sK + rr * 104 + 64 + rc * 8) = R.k2;
;   *(u32x4*)(sVt + row * 72 + kc * 8) = R.v0;
; }
; DI void phase_attn_mla(const Params& P, bf16_t* og, unsigned char* smem, int L, int G) {
;     ...
;     for (int j = 0; j <= jhi; ++j) {
;       const int key0 = j * 64, cb = j & 1;
;       __syncthreads();
;       if (j < jhi) kv96x8_store(R, sK + (cb ^ 1) * KVB96, sVt + (cb ^ 1) * KVB96, tid);
;       if (j + 1 < jhi) kv96x8_fetch(R, knb, krb, vb, key0 + 128, tid);
;       __builtin_amdgcn_sched_barrier(0);
;       if (key0 <= t0 + 31) {
;         auto mf = [&](int kk) { return key0 + kk <= t; };
;         if (key0 + 63 > t0) attn_step<96, true, 0>(sK + cb * KVB96, sVt + cb * KVB96, qf, o0, o1, m, l, sc, mf, lane, s, 0.f);
;         else attn_step<96, false, 0>(sK + cb * KVB96, sVt + cb * KVB96, qf, o0, o1, m, l, sc, mf, lane, s, 0.f);
.LBB0_779:
	s_and_b32 s40, s26, 1
	s_waitcnt lgkmcnt(0)
	s_barrier
	s_add_i32 s27, s26, 1
	s_cmp_eq_u32 s101, 0
	s_cbranch_scc1 .Lmy_mla_early
	v_readfirstlane_b32 s100, v163
	s_nop 3
	s_cmp_le_i32 s14, s100
	s_cbranch_scc1 .LBB0_785
.Lmy_mla_early:
	s_cmp_ge_u32 s26, s19
	s_cbranch_scc1 .LBB0_783
	s_xor_b32 s24, s40, 1
	s_mulk_i32 s24, 0x2c00
	s_lshl_b32 s25, s24, 1
	v_add3_u32 v0, s25, v180, v158
	s_waitcnt vmcnt(1)
	ds_write_b128 v0, v[108:111]
	s_and_saveexec_b64 s[22:23], s[12:13]
	v_add3_u32 v0, s25, v151, v160
	ds_write_b128 v0, v[104:107] offset:128
	s_or_b64 exec, exec, s[22:23]
	v_lshl_add_u32 v0, s24, 1, v142
	s_waitcnt vmcnt(0)
	ds_write_b128 v0, v[112:115] offset:13312
.LBB0_783:
	s_cmp_ge_u32 s27, s19
	s_cbranch_scc1 .LBB0_785
	v_add_u32_e32 v2, s14, v179
	v_ashrrev_i32_e32 v3, 31, v2
	v_lshlrev_b64 v[2:3], 11, v[2:3]
	v_add_u32_e32 v0, s14, v178
	v_lshl_add_u64 v[2:3], v[168:169], 0, v[2:3]
	v_lshlrev_b64 v[4:5], 6, v[0:1]
	v_lshl_add_u64 v[4:5], v[170:171], 0, v[4:5]
	global_load_dwordx4 v[108:111], v[2:3], off
	global_load_dwordx4 v[104:107], v[4:5], off
	v_lshl_add_u64 v[2:3], s[14:15], 1, v[166:167]
	global_load_dwordx4 v[112:115], v[2:3], off offset:256
.LBB0_785:
	v_cmp_le_i32_e32 vcc, s14, v163
	s_and_saveexec_b64 s[22:23], vcc
	s_cbranch_execz .LBB0_791
	s_add_i32 s24, s14, 63
	s_mulk_i32 s40, 0x2c00
	v_cmp_le_i32_e32 vcc, s24, v162
	s_lshl_b32 s39, s40, 1
	v_max_f32_e32 v0, v186, v186
	s_and_saveexec_b64 s[24:25], vcc
	s_xor_b64 s[24:25], exec, s[24:25]
	s_cbranch_execz .LBB0_788
	v_lshl_add_u32 v14, s40, 1, v143
	ds_read_b128 v[2:5], v14
	ds_read_b128 v[6:9], v14 offset:32
	ds_read_b128 v[10:13], v14 offset:64
	ds_read_b128 v[116:119], v14 offset:96
	ds_read_b128 v[120:123], v14 offset:128
	ds_read_b128 v[124:127], v14 offset:160
	ds_read_b128 v[48:51], v14 offset:6656
	ds_read_b128 v[128:131], v14 offset:6688
	ds_read_b128 v[132:135], v14 offset:6720
	ds_read_b128 v[188:191], v14 offset:6752
	ds_read_b128 v[194:197], v14 offset:6784
	ds_read_b128 v[198:201], v14 offset:6816
	s_waitcnt lgkmcnt(11)
	v_mfma_f32_32x32x16_bf16 v[64:79], v[2:5], v[100:103], 0
	v_add3_u32 v2, s39, v172, v156
	v_add3_u32 v3, s39, v173, v156
	s_waitcnt lgkmcnt(10)
	v_mfma_f32_32x32x16_bf16 v[64:79], v[6:9], v[80:83], v[64:79]
	s_waitcnt lgkmcnt(5)
	v_mfma_f32_32x32x16_bf16 v[48:63], v[48:51], v[100:103], 0
	v_mfma_f32_32x32x16_bf16 v[64:79], v[10:13], v[84:87], v[64:79]
	s_waitcnt lgkmcnt(4)
	v_mfma_f32_32x32x16_bf16 v[48:63], v[128:131], v[80:83], v[48:63]
	v_mfma_f32_32x32x16_bf16 v[64:79], v[116:119], v[88:91], v[64:79]
	s_waitcnt lgkmcnt(3)
	v_mfma_f32_32x32x16_bf16 v[48:63], v[132:135], v[84:87], v[48:63]
	v_mfma_f32_32x32x16_bf16 v[64:79], v[120:123], v[92:95], v[64:79]
	s_waitcnt lgkmcnt(2)
	v_mfma_f32_32x32x16_bf16 v[48:63], v[188:191], v[88:91], v[48:63]
	v_mfma_f32_32x32x16_bf16 v[64:79], v[124:127], v[96:99], v[64:79]
	ds_read_b128 v[132:135], v2 offset:13312
	ds_read_b128 v[124:127], v2 offset:13344
	ds_read_b128 v[128:131], v3 offset:13312
	ds_read_b128 v[120:123], v3 offset:13344
	ds_read_b128 v[116:119], v2 offset:13376
	ds_read_b128 v[6:9], v2 offset:13408
	ds_read_b128 v[10:13], v3 offset:13376
	ds_read_b128 v[2:5], v3 offset:13408
	s_waitcnt lgkmcnt(9)
	v_mfma_f32_32x32x16_bf16 v[48:63], v[194:197], v[92:95], v[48:63]
	s_waitcnt lgkmcnt(8)
	v_mfma_f32_32x32x16_bf16 v[48:63], v[198:201], v[96:99], v[48:63]
	s_cmp_eq_u32 s101, 0
	s_cbranch_scc1 .Lmy_mla_b1_end
	s_cmp_ge_u32 s26, s19
	s_cbranch_scc1 .Lmy_mla_b1_f
	s_and_b32 s98, s26, 1
	s_xor_b32 s98, s98, 1
	s_mulk_i32 s98, 0x2c00
	s_lshl_b32 s99, s98, 1
	v_add3_u32 v202, s99, v180, v158
	s_waitcnt vmcnt(1)
	ds_write_b128 v202, v[108:111]
	v_lshl_add_u32 v202, s98, 1, v142
	s_waitcnt vmcnt(0)
	ds_write_b128 v202, v[112:115] offset:13312
.Lmy_mla_b1_f:
	s_cmp_ge_u32 s27, s19
	s_cbranch_scc1 .Lmy_mla_b1_end
	v_add_u32_e32 v204, s14, v179
	v_ashrrev_i32_e32 v205, 31, v204
	v_lshlrev_b64 v[204:205], 11, v[204:205]
	v_add_u32_e32 v206, s14, v178
	v_mov_b32_e32 v207, 0
	v_lshl_add_u64 v[204:205], v[168:169], 0, v[204:205]
	v_lshlrev_b64 v[206:207], 6, v[206:207]
	v_lshl_add_u64 v[206:207], v[170:171], 0, v[206:207]
	global_load_dwordx4 v[108:111], v[204:205], off
	global_load_dwordx4 v[104:107], v[206:207], off
	v_lshl_add_u64 v[204:205], s[14:15], 1, v[166:167]
	global_load_dwordx4 v[112:115], v[204:205], off offset:256
; #define MFMA(a, b, c) __builtin_amdgcn_mfma_f32_32x32x16_bf16((a), (b), (c), 0, 0, 0)
; DI unsigned pack2(float a, float b) { f32x2_t v = {a, b}; bf16x2_t r = __builtin_convertvector(v, bf16x2_t); return __builtin_bit_cast(unsigned, r); }
; DI float fexp2(float x) { return __builtin_amdgcn_exp2f(x); }
; DI float shx(float v, int m) { return __shfl_xor(v, m, 64); }
; template <int DQK, bool MASKED, int MODE, class MF>
; DI void attn_step(const bf16_t* sK, const bf16_t* sVt, const bf16x8 (&qf)[DQK / 16], f32x16& o0, f32x16& o1, float& m, float& l,
;                   float sc, const MF& mf, int lane, f32x16 (&s)[2], float invl, bool lanevalid = true) {
;     ...
;   float mxr = -3.0e38f;
; #pragma unroll
;   for (int sub = 0; sub < 2; ++sub)
; #pragma unroll
;     for (int q = 0; q < 16; ++q) {
;       if (MASKED) { const int kk = sub * 32 + 16 * (q >> 3) + 8 * h + (q & 7); s[sub][q] = mf(kk) ? s[sub][q] : -3.0e38f; }
;       if (MODE != 2) mxr = fmaxf(mxr, s[sub][q]);
;     }
;   float alpha = 1.f;
;   if (MODE != 2) {
;     float mx = fmaxf(m, mxr * sc);
;     mx = fmaxf(mx, shx(mx, 32));
;     if (!MASKED) mx = lanevalid ? mx : m;
;     alpha = fexp2(m - mx);
;     m = mx;
;   }
;   const float moff = (!MASKED && !lanevalid) ? 1.0e30f : m;
;   float ps = 0.f;
; #pragma unroll
;   for (int sub = 0; sub < 2; ++sub)
; #pragma unroll
;     for (int q = 0; q < 16; ++q) {
;       float pv = fexp2(__builtin_fmaf(s[sub][q], sc, -moff));
;       if (MASKED && MODE != 0) pv = (s[sub][q] > -1.0e38f) ? pv : 0.f;
;       if (MODE == 2) pv *= invl;
;       s[sub][q] = pv;
;       ps += pv;
;     }
;   if (MODE != 2) {
;     ps += shx(ps, 32);
;     l = l * alpha + ps;
;   }
;   if (MODE == 1) return;
;   if (MODE == 0) {
; #pragma unroll
;     for (int q = 0; q < 16; ++q) { o0[q] *= alpha; o1[q] *= alpha; }
;   }
; #pragma unroll
;   for (int sub = 0; sub < 2; ++sub)
; #pragma unroll
;     for (int s2 = 0; s2 < 2; ++s2) {
;       union { bf16x8 v; unsigned u[4]; } pb;
; #pragma unroll
;       for (int e = 0; e < 4; ++e) pb.u[e] = pack2(s[sub][8 * s2 + 2 * e], s[sub][8 * s2 + 2 * e + 1]);
;       o0 = MFMA(vf[sub][s2][0], pb.v, o0);
;       o1 = MFMA(vf[sub][s2][1], pb.v, o1);
;     }
.Lmy_mla_b1_end:
	v_max3_f32 v14, v64, s36, v65
	v_max3_f32 v14, v14, v66, v67
	v_max3_f32 v14, v14, v68, v69
	v_max3_f32 v14, v14, v70, v71
	v_max3_f32 v14, v14, v72, v73
	v_max3_f32 v14, v14, v74, v75
	v_max3_f32 v14, v14, v76, v77
	v_max3_f32 v14, v14, v78, v79
	s_nop 3
	v_max3_f32 v14, v14, v48, v49
	v_max3_f32 v14, v14, v50, v51
	v_max3_f32 v14, v14, v52, v53
	v_max3_f32 v14, v14, v54, v55
	v_max3_f32 v14, v14, v56, v57
	v_max3_f32 v14, v14, v58, v59
	v_max3_f32 v14, v14, v60, v61
	v_max3_f32 v14, v14, v62, v63
	v_mul_f32_e32 v14, 0x3e16c740, v14
	v_cmp_lt_i32_e32 vcc, v183, v184
	v_max_f32_e32 v0, v0, v14
	s_nop 0
	v_cndmask_b32_e32 v14, v182, v183, vcc
	v_lshlrev_b32_e32 v14, 2, v14
	ds_bpermute_b32 v15, v14, v0
	s_waitcnt lgkmcnt(0)
	v_max_f32_e32 v15, v15, v15
	v_max_f32_e32 v15, v0, v15
	v_fma_f32 v0, v64, s37, -v15
	v_fma_f32 v64, v65, s37, -v15
	v_exp_f32_e32 v65, v0
	v_exp_f32_e32 v64, v64
	v_fma_f32 v0, v66, s37, -v15
	v_exp_f32_e32 v66, v0
	v_fma_f32 v67, v67, s37, -v15
	v_exp_f32_e32 v67, v67
	v_fma_f32 v68, v68, s37, -v15
	v_sub_f32_e32 v0, v186, v15
	v_add_f32_e32 v186, 0, v65
	v_exp_f32_e32 v68, v68
	v_fma_f32 v69, v69, s37, -v15
	v_add_f32_e32 v186, v64, v186
	v_exp_f32_e32 v69, v69
	v_fma_f32 v70, v70, s37, -v15
	v_add_f32_e32 v186, v66, v186
	v_exp_f32_e32 v70, v70
	v_fma_f32 v71, v71, s37, -v15
	v_add_f32_e32 v186, v67, v186
	v_exp_f32_e32 v71, v71
	v_fma_f32 v72, v72, s37, -v15
	v_add_f32_e32 v186, v68, v186
	v_exp_f32_e32 v72, v72
	v_fma_f32 v73, v73, s37, -v15
	v_add_f32_e32 v186, v69, v186
	v_exp_f32_e32 v73, v73
	v_fma_f32 v74, v74, s37, -v15
	v_add_f32_e32 v186, v70, v186
	v_exp_f32_e32 v74, v74
	v_fma_f32 v75, v75, s37, -v15
	v_add_f32_e32 v186, v71, v186
	v_exp_f32_e32 v75, v75
	v_fma_f32 v76, v76, s37, -v15
	v_add_f32_e32 v186, v72, v186
	v_exp_f32_e32 v76, v76
	v_fma_f32 v77, v77, s37, -v15
	v_add_f32_e32 v186, v73, v186
	v_exp_f32_e32 v77, v77
	v_fma_f32 v78, v78, s37, -v15
	v_add_f32_e32 v186, v74, v186
	v_exp_f32_e32 v78, v78
	v_fma_f32 v79, v79, s37, -v15
	v_add_f32_e32 v186, v75, v186
	v_exp_f32_e32 v79, v79
	v_fma_f32 v48, v48, s37, -v15
	v_add_f32_e32 v186, v76, v186
	v_exp_f32_e32 v187, v48
	v_fma_f32 v48, v49, s37, -v15
	v_add_f32_e32 v186, v77, v186
	v_exp_f32_e32 v188, v48
	v_fma_f32 v48, v50, s37, -v15
	v_add_f32_e32 v186, v78, v186
	v_exp_f32_e32 v189, v48
	v_fma_f32 v49, v51, s37, -v15
	v_add_f32_e32 v48, v79, v186
	v_exp_f32_e32 v186, v49
	v_fma_f32 v49, v52, s37, -v15
	v_add_f32_e32 v48, v187, v48
	v_exp_f32_e32 v52, v49
	v_fma_f32 v49, v53, s37, -v15
	v_add_f32_e32 v48, v188, v48
	v_exp_f32_e32 v53, v49
	v_fma_f32 v49, v54, s37, -v15
	v_add_f32_e32 v48, v189, v48
	v_exp_f32_e32 v54, v49
	v_add_f32_e32 v48, v186, v48
	v_add_f32_e32 v48, v52, v48
	v_exp_f32_e32 v0, v0
	v_add_f32_e32 v48, v53, v48
	v_add_f32_e32 v190, v54, v48
	v_fma_f32 v48, v55, s37, -v15
	v_exp_f32_e32 v55, v48
	v_fma_f32 v48, v56, s37, -v15
	v_exp_f32_e32 v56, v48
	v_pk_mul_f32 v[46:47], v[46:47], v[0:1] op_sel_hi:[1,0]
	v_pk_mul_f32 v[44:45], v[44:45], v[0:1] op_sel_hi:[1,0]
	v_pk_mul_f32 v[42:43], v[42:43], v[0:1] op_sel_hi:[1,0]
	v_pk_mul_f32 v[40:41], v[40:41], v[0:1] op_sel_hi:[1,0]
	v_pk_mul_f32 v[38:39], v[38:39], v[0:1] op_sel_hi:[1,0]
	v_pk_mul_f32 v[36:37], v[36:37], v[0:1] op_sel_hi:[1,0]
	v_pk_mul_f32 v[34:35], v[34:35], v[0:1] op_sel_hi:[1,0]
	v_pk_mul_f32 v[32:33], v[32:33], v[0:1] op_sel_hi:[1,0]
	v_cvt_pk_bf16_f32 v48, v65, v64
	v_cvt_pk_bf16_f32 v49, v66, v67
	v_cvt_pk_bf16_f32 v50, v68, v69
	v_cvt_pk_bf16_f32 v51, v70, v71
	v_pk_mul_f32 v[30:31], v[30:31], v[0:1] op_sel_hi:[1,0]
	v_pk_mul_f32 v[28:29], v[28:29], v[0:1] op_sel_hi:[1,0]
	v_mfma_f32_32x32x16_bf16 v[32:47], v[132:135], v[48:51], v[32:47]
	v_mul_f32_e64 v26, v26, v0
	v_mul_f32_e64 v27, v27, v0
	v_mul_f32_e64 v24, v24, v0
	v_mul_f32_e64 v25, v25, v0
	v_mul_f32_e64 v22, v22, v0
	v_mul_f32_e64 v23, v23, v0
	v_pk_mul_f32 v[20:21], v[20:21], v[0:1] op_sel_hi:[1,0]
	v_pk_mul_f32 v[18:19], v[18:19], v[0:1] op_sel_hi:[1,0]
	v_pk_mul_f32 v[16:17], v[16:17], v[0:1] op_sel_hi:[1,0]
	v_fma_f32 v57, v57, s37, -v15
	v_exp_f32_e32 v57, v57
	v_mfma_f32_32x32x16_bf16 v[16:31], v[128:131], v[48:51], v[16:31]
	v_add_f32_e32 v48, v55, v190
	v_add_f32_e32 v64, v56, v48
	v_cvt_pk_bf16_f32 v48, v72, v73
	v_cvt_pk_bf16_f32 v49, v74, v75
	v_cvt_pk_bf16_f32 v50, v76, v77
	v_cvt_pk_bf16_f32 v51, v78, v79
	v_fma_f32 v58, v58, s37, -v15
	v_exp_f32_e32 v58, v58
	v_mfma_f32_32x32x16_bf16 v[32:47], v[124:127], v[48:51], v[32:47]
	v_fma_f32 v59, v59, s37, -v15
	v_exp_f32_e32 v59, v59
	v_add_f32_e32 v64, v57, v64
	v_add_f32_e32 v64, v58, v64
	v_add_f32_e32 v64, v59, v64
	v_mfma_f32_32x32x16_bf16 v[16:31], v[120:123], v[48:51], v[16:31]
	v_fma_f32 v48, v60, s37, -v15
	v_exp_f32_e32 v60, v48
	v_cvt_pk_bf16_f32 v48, v187, v188
	v_cvt_pk_bf16_f32 v49, v189, v186
	v_cvt_pk_bf16_f32 v50, v52, v53
	v_cvt_pk_bf16_f32 v51, v54, v55
	v_fma_f32 v53, v61, s37, -v15
	v_exp_f32_e32 v53, v53
	v_mfma_f32_32x32x16_bf16 v[32:47], v[116:119], v[48:51], v[32:47]
	v_fma_f32 v54, v62, s37, -v15
	v_exp_f32_e32 v54, v54
	v_fma_f32 v55, v63, s37, -v15
	v_exp_f32_e32 v55, v55
	v_add_f32_e32 v52, v60, v64
	v_mov_b32_e32 v186, v15
	v_mfma_f32_32x32x16_bf16 v[16:31], v[10:13], v[48:51], v[16:31]
	v_add_f32_e32 v10, v53, v52
	v_add_f32_e32 v10, v54, v10
	v_add_f32_e32 v48, v55, v10
	v_cvt_pk_bf16_f32 v10, v56, v57
	v_cvt_pk_bf16_f32 v11, v58, v59
	v_cvt_pk_bf16_f32 v12, v60, v53
	v_cvt_pk_bf16_f32 v13, v54, v55
	s_nop 1
	v_mfma_f32_32x32x16_bf16 v[32:47], v[6:9], v[10:13], v[32:47]
	ds_bpermute_b32 v6, v14, v48
	s_waitcnt lgkmcnt(0)
	v_add_f32_e32 v6, v48, v6
	v_fmac_f32_e32 v6, v165, v0
	v_mfma_f32_32x32x16_bf16 v[16:31], v[2:5], v[10:13], v[16:31]
	v_mov_b32_e32 v165, v6
; #define MFMA(a, b, c) __builtin_amdgcn_mfma_f32_32x32x16_bf16((a), (b), (c), 0, 0, 0)
; DI int kperm(int r) { return (r & 0x13) | ((r & 8) >> 1) | ((r & 4) << 1); }
; template <int DQK, bool MASKED, int MODE, class MF>
; DI void attn_step(const bf16_t* sK, const bf16_t* sVt, const bf16x8 (&qf)[DQK / 16], f32x16& o0, f32x16& o1, float& m, float& l,
;                   float sc, const MF& mf, int lane, f32x16 (&s)[2], float invl, bool lanevalid = true) {
;     ...
;   const int pr = kperm(r);
;   constexpr int KST = DQK + 8;
;   bf16x8 kf[2][DQK / 16];
; #pragma unroll
;   for (int sub = 0; sub < 2; ++sub)
; #pragma unroll
;     for (int ks = 0; ks < DQK / 16; ++ks) kf[sub][ks] = *(const bf16x8*)(sK + (sub * 32 + pr) * KST + ks * 16 + 8 * h);
;   __builtin_amdgcn_sched_barrier(0);
; #pragma unroll
;   for (int q = 0; q < 16; ++q) { s[0][q] = 0.f; s[1][q] = 0.f; }
; #pragma unroll
;   for (int ks = 0; ks < DQK / 16; ++ks) {
;     s[0] = MFMA(kf[0][ks], qf[ks], s[0]);
;     s[1] = MFMA(kf[1][ks], qf[ks], s[1]);
;   }
; DI void kv96x8_store(const KVR8& R, bf16_t* sK, bf16_t* sVt, int tid) {
;   const int row = tid >> 3, kc = tid & 7, rr = (tid & 255) >> 2, rc = tid & 3;
;   *(u32x4*)(sK + row * 104 + kc * 8) = R.k0;
;   if (tid < 256) *(u32x4*)(sK + rr * 104 + 64 + rc * 8) = R.k2;
;   *(u32x4*)(sVt + row * 72 + kc * 8) = R.v0;
; }
.LBB0_788:
	s_andn2_saveexec_b64 s[24:25], s[24:25]
	s_cbranch_execz .LBB0_790
	v_lshl_add_u32 v14, s40, 1, v176
	ds_read_b128 v[2:5], v14
	ds_read_b128 v[6:9], v14 offset:32
	ds_read_b128 v[10:13], v14 offset:64
	ds_read_b128 v[116:119], v14 offset:96
	ds_read_b128 v[120:123], v14 offset:128
	ds_read_b128 v[124:127], v14 offset:160
	ds_read_b128 v[48:51], v14 offset:6656
	ds_read_b128 v[128:131], v14 offset:6688
	ds_read_b128 v[132:135], v14 offset:6720
	ds_read_b128 v[188:191], v14 offset:6752
	ds_read_b128 v[194:197], v14 offset:6784
	ds_read_b128 v[198:201], v14 offset:6816
	s_waitcnt lgkmcnt(11)
	v_mfma_f32_32x32x16_bf16 v[64:79], v[2:5], v[100:103], 0
	v_lshlrev_b32_e32 v2, 1, v175
	v_add3_u32 v3, s39, v172, v2
	v_add3_u32 v2, s39, v173, v2
	s_waitcnt lgkmcnt(10)
	v_mfma_f32_32x32x16_bf16 v[64:79], v[6:9], v[80:83], v[64:79]
	s_waitcnt lgkmcnt(5)
	v_mfma_f32_32x32x16_bf16 v[48:63], v[48:51], v[100:103], 0
	v_mfma_f32_32x32x16_bf16 v[64:79], v[10:13], v[84:87], v[64:79]
	s_waitcnt lgkmcnt(4)
	v_mfma_f32_32x32x16_bf16 v[48:63], v[128:131], v[80:83], v[48:63]
	v_mfma_f32_32x32x16_bf16 v[64:79], v[116:119], v[88:91], v[64:79]
	s_waitcnt lgkmcnt(3)
	v_mfma_f32_32x32x16_bf16 v[48:63], v[132:135], v[84:87], v[48:63]
	v_mfma_f32_32x32x16_bf16 v[64:79], v[120:123], v[92:95], v[64:79]
	s_waitcnt lgkmcnt(2)
	v_mfma_f32_32x32x16_bf16 v[48:63], v[188:191], v[88:91], v[48:63]
	v_mfma_f32_32x32x16_bf16 v[64:79], v[124:127], v[96:99], v[64:79]
	ds_read_b128 v[132:135], v3 offset:13312
	ds_read_b128 v[124:127], v3 offset:13344
	ds_read_b128 v[128:131], v2 offset:13312
	ds_read_b128 v[120:123], v2 offset:13344
	ds_read_b128 v[116:119], v3 offset:13376
	ds_read_b128 v[6:9], v3 offset:13408
	ds_read_b128 v[10:13], v2 offset:13376
	ds_read_b128 v[2:5], v2 offset:13408
	s_waitcnt lgkmcnt(9)
	v_mfma_f32_32x32x16_bf16 v[48:63], v[194:197], v[92:95], v[48:63]
	s_waitcnt lgkmcnt(8)
	v_mfma_f32_32x32x16_bf16 v[48:63], v[198:201], v[96:99], v[48:63]
	s_cmp_eq_u32 s101, 0
	s_cbranch_scc1 .Lmy_mla_b0_end
	s_cmp_ge_u32 s26, s19
	s_cbranch_scc1 .Lmy_mla_b0_f
	s_and_b32 s98, s26, 1
	s_xor_b32 s98, s98, 1
	s_mulk_i32 s98, 0x2c00
	s_lshl_b32 s99, s98, 1
	v_add3_u32 v202, s99, v180, v158
	s_waitcnt vmcnt(1)
	ds_write_b128 v202, v[108:111]
	v_lshl_add_u32 v202, s98, 1, v142
	s_waitcnt vmcnt(0)
	ds_write_b128 v202, v[112:115] offset:13312

; DI float fexp2(float x) { return __builtin_amdgcn_exp2f(x); }
; DI float shx(float v, int m) { return __shfl_xor(v, m, 64); }
; template <int DQK, bool MASKED, int MODE, class MF>
; DI void attn_step(const bf16_t* sK, const bf16_t* sVt, const bf16x8 (&qf)[DQK / 16], f32x16& o0, f32x16& o1, float& m, float& l,
;                   float sc, const MF& mf, int lane, f32x16 (&s)[2], float invl, bool lanevalid = true) {
;     ...
;   float mxr = -3.0e38f;
; #pragma unroll
;   for (int sub = 0; sub < 2; ++sub)
; #pragma unroll
;     for (int q = 0; q < 16; ++q) {
;       if (MASKED) { const int kk = sub * 32 + 16 * (q >> 3) + 8 * h + (q & 7); s[sub][q] = mf(kk) ? s[sub][q] : -3.0e38f; }
;       if (MODE != 2) mxr = fmaxf(mxr, s[sub][q]);
;     }
;   float alpha = 1.f;
;   if (MODE != 2) {
;     float mx = fmaxf(m, mxr * sc);
;     mx = fmaxf(mx, shx(mx, 32));
;     if (!MASKED) mx = lanevalid ? mx : m;
;     alpha = fexp2(m - mx);
;     m = mx;
;   }
.Lmy_mla_b0_end:
	v_add_u32_e32 v14, s14, v175
	v_cmp_le_i32_e32 vcc, v14, v164
	s_nop 1
	v_cndmask_b32_e32 v15, v185, v64, vcc
	v_cmp_lt_i32_e32 vcc, v14, v164
	s_nop 1
	v_cndmask_b32_e32 v64, v185, v65, vcc
	v_add_u32_e32 v65, 2, v14
	v_cmp_le_i32_e32 vcc, v65, v164
	s_nop 1
	v_cndmask_b32_e32 v65, v185, v66, vcc
	v_add_u32_e32 v66, 3, v14
	v_cmp_le_i32_e32 vcc, v66, v164
	s_nop 1
	v_cndmask_b32_e32 v66, v185, v67, vcc
	v_add_u32_e32 v67, 4, v14
	v_cmp_le_i32_e32 vcc, v67, v164
	s_nop 1
	v_cndmask_b32_e32 v67, v185, v68, vcc
	v_add_u32_e32 v68, 5, v14
	v_cmp_le_i32_e32 vcc, v68, v164
	s_nop 1
	v_cndmask_b32_e32 v68, v185, v69, vcc
	v_add_u32_e32 v69, 6, v14
	v_cmp_le_i32_e32 vcc, v69, v164
	s_nop 1
	v_cndmask_b32_e32 v69, v185, v70, vcc
	v_add_u32_e32 v70, s14, v174
	v_or_b32_e32 v187, 7, v70
	v_cmp_le_i32_e32 vcc, v187, v164
	v_add_u32_e32 v187, 16, v14
	s_nop 0
	v_cndmask_b32_e32 v71, v185, v71, vcc
	v_cmp_le_i32_e32 vcc, v187, v164
	v_add_u32_e32 v187, 17, v14
	s_nop 0
	v_cndmask_b32_e32 v72, v185, v72, vcc
	v_cmp_le_i32_e32 vcc, v187, v164
	v_add_u32_e32 v187, 18, v14
	s_nop 0
	v_cndmask_b32_e32 v73, v185, v73, vcc
	v_cmp_le_i32_e32 vcc, v187, v164
	v_add_u32_e32 v187, 19, v14
	s_nop 0
	v_cndmask_b32_e32 v74, v185, v74, vcc
	v_cmp_le_i32_e32 vcc, v187, v164
	v_add_u32_e32 v187, 20, v14
	s_nop 0
	v_cndmask_b32_e32 v75, v185, v75, vcc
	v_cmp_le_i32_e32 vcc, v187, v164
	v_add_u32_e32 v187, 21, v14
	s_nop 0
	v_cndmask_b32_e32 v76, v185, v76, vcc
	v_cmp_le_i32_e32 vcc, v187, v164
	v_add_u32_e32 v187, 22, v14
	s_nop 0
	v_cndmask_b32_e32 v77, v185, v77, vcc
	v_cmp_le_i32_e32 vcc, v187, v164
	v_or_b32_e32 v187, 23, v70
	s_nop 0
	v_cndmask_b32_e32 v78, v185, v78, vcc
	v_cmp_le_i32_e32 vcc, v187, v164
	v_add_u32_e32 v187, 32, v14
	s_nop 0
	v_cndmask_b32_e32 v79, v185, v79, vcc
	v_cmp_le_i32_e32 vcc, v187, v164
	v_add_u32_e32 v187, 33, v14
	s_nop 0
	v_cndmask_b32_e32 v48, v185, v48, vcc
	v_cmp_le_i32_e32 vcc, v187, v164
	v_add_u32_e32 v187, 34, v14
	s_nop 0
	v_cndmask_b32_e32 v49, v185, v49, vcc
	v_cmp_le_i32_e32 vcc, v187, v164
	v_add_u32_e32 v187, 35, v14
	s_nop 0
	v_cndmask_b32_e32 v50, v185, v50, vcc
	v_cmp_le_i32_e32 vcc, v187, v164
	v_add_u32_e32 v187, 36, v14
	s_nop 0
	v_cndmask_b32_e32 v51, v185, v51, vcc
	v_cmp_le_i32_e32 vcc, v187, v164
	v_add_u32_e32 v187, 37, v14
	s_nop 0
	v_cndmask_b32_e32 v52, v185, v52, vcc
	v_cmp_le_i32_e32 vcc, v187, v164
	v_add_u32_e32 v187, 38, v14
	s_nop 0
	v_cndmask_b32_e32 v53, v185, v53, vcc
	v_cmp_le_i32_e32 vcc, v187, v164
	v_or_b32_e32 v187, 39, v70
	s_nop 0
	v_cndmask_b32_e32 v54, v185, v54, vcc
	v_cmp_le_i32_e32 vcc, v187, v164
	v_add_u32_e32 v187, 48, v14
	s_nop 0
	v_cndmask_b32_e32 v55, v185, v55, vcc
	v_cmp_le_i32_e32 vcc, v187, v164
	v_add_u32_e32 v187, 49, v14
	s_nop 0
	v_cndmask_b32_e32 v56, v185, v56, vcc
	v_cmp_le_i32_e32 vcc, v187, v164
	v_add_u32_e32 v187, 50, v14
	s_nop 0
	v_cndmask_b32_e32 v57, v185, v57, vcc
	v_cmp_le_i32_e32 vcc, v187, v164
	v_add_u32_e32 v187, 51, v14
	s_nop 0
	v_cndmask_b32_e32 v58, v185, v58, vcc
	v_cmp_le_i32_e32 vcc, v187, v164
	v_add_u32_e32 v187, 52, v14
	s_nop 0
	v_cndmask_b32_e32 v59, v185, v59, vcc
	v_cmp_le_i32_e32 vcc, v187, v164
	v_add_u32_e32 v187, 53, v14
	v_add_u32_e32 v14, 54, v14
	v_cndmask_b32_e32 v60, v185, v60, vcc
	v_cmp_le_i32_e32 vcc, v187, v164
	s_nop 1
	v_cndmask_b32_e32 v61, v185, v61, vcc
	v_cmp_le_i32_e32 vcc, v14, v164
	s_nop 1
	v_cndmask_b32_e32 v14, v185, v62, vcc
	v_or_b32_e32 v62, 55, v70
	v_cmp_le_i32_e32 vcc, v62, v164
	s_nop 1
	v_cndmask_b32_e32 v62, v185, v63, vcc
	v_max3_f32 v63, v15, s36, v64
	v_max3_f32 v63, v63, v65, v66
	v_max3_f32 v63, v63, v67, v68
	v_max3_f32 v63, v63, v69, v71
	v_max3_f32 v63, v63, v72, v73
	v_max3_f32 v63, v63, v74, v75
	v_max3_f32 v63, v63, v76, v77
	v_max3_f32 v63, v63, v78, v79
	v_max3_f32 v63, v63, v48, v49
	v_max3_f32 v63, v63, v50, v51
	v_max3_f32 v63, v63, v52, v53
	v_max3_f32 v63, v63, v54, v55
	v_max3_f32 v63, v63, v56, v57
	v_max3_f32 v63, v63, v58, v59
	v_max3_f32 v63, v63, v60, v61
	v_max3_f32 v63, v63, v14, v62
	v_mul_f32_e32 v63, 0x3e16c740, v63
	v_cmp_lt_i32_e32 vcc, v183, v184
	v_max_f32_e32 v0, v0, v63
	s_nop 0
	v_cndmask_b32_e32 v63, v182, v183, vcc
	v_lshlrev_b32_e32 v63, 2, v63
	ds_bpermute_b32 v70, v63, v0
	s_waitcnt lgkmcnt(0)
; #define MFMA(a, b, c) __builtin_amdgcn_mfma_f32_32x32x16_bf16((a), (b), (c), 0, 0, 0)
; DI unsigned pack2(float a, float b) { f32x2_t v = {a, b}; bf16x2_t r = __builtin_convertvector(v, bf16x2_t); return __builtin_bit_cast(unsigned, r); }
; DI float fexp2(float x) { return __builtin_amdgcn_exp2f(x); }
; DI float shx(float v, int m) { return __shfl_xor(v, m, 64); }
; template <int DQK, bool MASKED, int MODE, class MF>
; DI void attn_step(const bf16_t* sK, const bf16_t* sVt, const bf16x8 (&qf)[DQK / 16], f32x16& o0, f32x16& o1, float& m, float& l,
;                   float sc, const MF& mf, int lane, f32x16 (&s)[2], float invl, bool lanevalid = true) {
;     ...
;   const float moff = (!MASKED && !lanevalid) ? 1.0e30f : m;
;   float ps = 0.f;
; #pragma unroll
;   for (int sub = 0; sub < 2; ++sub)
; #pragma unroll
;     for (int q = 0; q < 16; ++q) {
;       float pv = fexp2(__builtin_fmaf(s[sub][q], sc, -moff));
;       if (MASKED && MODE != 0) pv = (s[sub][q] > -1.0e38f) ? pv : 0.f;
;       if (MODE == 2) pv *= invl;
;       s[sub][q] = pv;
;       ps += pv;
;     }
;   if (MODE != 2) {
;     ps += shx(ps, 32);
;     l = l * alpha + ps;
;   }
;   if (MODE == 1) return;
;   if (MODE == 0) {
; #pragma unroll
;     for (int q = 0; q < 16; ++q) { o0[q] *= alpha; o1[q] *= alpha; }
;   }
; #pragma unroll
;   for (int sub = 0; sub < 2; ++sub)
; #pragma unroll
;     for (int s2 = 0; s2 < 2; ++s2) {
;       union { bf16x8 v; unsigned u[4]; } pb;
; #pragma unroll
;       for (int e = 0; e < 4; ++e) pb.u[e] = pack2(s[sub][8 * s2 + 2 * e], s[sub][8 * s2 + 2 * e + 1]);
;       o0 = MFMA(vf[sub][s2][0], pb.v, o0);
;       o1 = MFMA(vf[sub][s2][1], pb.v, o1);
;     }
	v_max_f32_e32 v70, v70, v70
	v_max_f32_e32 v70, v0, v70
	v_fma_f32 v0, v15, s37, -v70
	v_exp_f32_e32 v15, v0
	v_fma_f32 v0, v64, s37, -v70
	v_exp_f32_e32 v64, v0
	v_fma_f32 v0, v65, s37, -v70
	v_exp_f32_e32 v65, v0
	v_fma_f32 v66, v66, s37, -v70
	v_exp_f32_e32 v66, v66
	v_fma_f32 v67, v67, s37, -v70
	v_sub_f32_e32 v0, v186, v70
	v_add_f32_e32 v186, 0, v15
	v_exp_f32_e32 v67, v67
	v_fma_f32 v68, v68, s37, -v70
	v_add_f32_e32 v186, v64, v186
	v_exp_f32_e32 v68, v68
	v_fma_f32 v69, v69, s37, -v70
	v_add_f32_e32 v186, v65, v186
	v_exp_f32_e32 v69, v69
	v_fma_f32 v71, v71, s37, -v70
	v_add_f32_e32 v186, v66, v186
	v_exp_f32_e32 v71, v71
	v_fma_f32 v72, v72, s37, -v70
	v_add_f32_e32 v186, v67, v186
	v_exp_f32_e32 v72, v72
	v_fma_f32 v73, v73, s37, -v70
	v_add_f32_e32 v186, v68, v186
	v_exp_f32_e32 v73, v73
	v_fma_f32 v74, v74, s37, -v70
	v_add_f32_e32 v186, v69, v186
	v_exp_f32_e32 v74, v74
	v_fma_f32 v75, v75, s37, -v70
	v_add_f32_e32 v186, v71, v186
	v_exp_f32_e32 v75, v75
	v_fma_f32 v76, v76, s37, -v70
	v_add_f32_e32 v186, v72, v186
	v_exp_f32_e32 v76, v76
	v_fma_f32 v77, v77, s37, -v70
	v_add_f32_e32 v186, v73, v186
	v_exp_f32_e32 v77, v77
	v_fma_f32 v78, v78, s37, -v70
	v_add_f32_e32 v186, v74, v186
	v_exp_f32_e32 v78, v78
	v_fma_f32 v79, v79, s37, -v70
	v_add_f32_e32 v186, v75, v186
	v_exp_f32_e32 v79, v79
	v_fma_f32 v48, v48, s37, -v70
	v_add_f32_e32 v186, v76, v186
	v_exp_f32_e32 v187, v48
	v_fma_f32 v48, v49, s37, -v70
	v_add_f32_e32 v186, v77, v186
	v_exp_f32_e32 v188, v48
	v_fma_f32 v48, v50, s37, -v70
	v_add_f32_e32 v186, v78, v186
	v_exp_f32_e32 v189, v48
	v_fma_f32 v49, v51, s37, -v70
	v_add_f32_e32 v48, v79, v186
	v_exp_f32_e32 v186, v49
	v_fma_f32 v49, v52, s37, -v70
	v_add_f32_e32 v48, v187, v48
	v_exp_f32_e32 v52, v49
	v_fma_f32 v49, v53, s37, -v70
	v_add_f32_e32 v48, v188, v48
	v_exp_f32_e32 v53, v49
	v_fma_f32 v49, v54, s37, -v70
	v_add_f32_e32 v48, v189, v48
	v_exp_f32_e32 v54, v49
	v_add_f32_e32 v48, v186, v48
	v_add_f32_e32 v48, v52, v48
	v_exp_f32_e32 v0, v0
	v_add_f32_e32 v48, v53, v48
	v_add_f32_e32 v190, v54, v48
	v_fma_f32 v48, v55, s37, -v70
	v_exp_f32_e32 v55, v48
	v_fma_f32 v48, v56, s37, -v70
	v_exp_f32_e32 v56, v48
	v_pk_mul_f32 v[46:47], v[46:47], v[0:1] op_sel_hi:[1,0]
	v_pk_mul_f32 v[44:45], v[44:45], v[0:1] op_sel_hi:[1,0]
	v_pk_mul_f32 v[42:43], v[42:43], v[0:1] op_sel_hi:[1,0]
	v_pk_mul_f32 v[40:41], v[40:41], v[0:1] op_sel_hi:[1,0]
	v_pk_mul_f32 v[38:39], v[38:39], v[0:1] op_sel_hi:[1,0]
	v_pk_mul_f32 v[36:37], v[36:37], v[0:1] op_sel_hi:[1,0]
	v_pk_mul_f32 v[34:35], v[34:35], v[0:1] op_sel_hi:[1,0]
	v_pk_mul_f32 v[32:33], v[32:33], v[0:1] op_sel_hi:[1,0]
	v_pk_mul_f32 v[30:31], v[30:31], v[0:1] op_sel_hi:[1,0]
	v_cvt_pk_bf16_f32 v48, v15, v64
	v_cvt_pk_bf16_f32 v49, v65, v66
	v_cvt_pk_bf16_f32 v50, v67, v68
	v_cvt_pk_bf16_f32 v51, v69, v71
	v_pk_mul_f32 v[28:29], v[28:29], v[0:1] op_sel_hi:[1,0]
	v_pk_mul_f32 v[26:27], v[26:27], v[0:1] op_sel_hi:[1,0]
	v_pk_mul_f32 v[24:25], v[24:25], v[0:1] op_sel_hi:[1,0]
	v_pk_mul_f32 v[22:23], v[22:23], v[0:1] op_sel_hi:[1,0]
	v_pk_mul_f32 v[20:21], v[20:21], v[0:1] op_sel_hi:[1,0]
	v_pk_mul_f32 v[18:19], v[18:19], v[0:1] op_sel_hi:[1,0]
	v_pk_mul_f32 v[16:17], v[16:17], v[0:1] op_sel_hi:[1,0]
	v_mfma_f32_32x32x16_bf16 v[32:47], v[132:135], v[48:51], v[32:47]
	v_fma_f32 v57, v57, s37, -v70
	v_exp_f32_e32 v57, v57
	v_fma_f32 v58, v58, s37, -v70
	v_exp_f32_e32 v58, v58
	v_fma_f32 v59, v59, s37, -v70
	v_add_f32_e32 v15, v55, v190
	v_exp_f32_e32 v59, v59
	v_mfma_f32_32x32x16_bf16 v[16:31], v[128:131], v[48:51], v[16:31]
	v_cvt_pk_bf16_f32 v48, v72, v73
	v_cvt_pk_bf16_f32 v49, v74, v75
	v_cvt_pk_bf16_f32 v50, v76, v77
	v_cvt_pk_bf16_f32 v51, v78, v79
	v_add_f32_e32 v15, v56, v15
	v_add_f32_e32 v15, v57, v15
	v_fma_f32 v14, v14, s37, -v70
	v_mfma_f32_32x32x16_bf16 v[32:47], v[124:127], v[48:51], v[32:47]
	v_add_f32_e32 v15, v58, v15
	v_exp_f32_e32 v14, v14
	v_add_f32_e32 v15, v59, v15
	v_mfma_f32_32x32x16_bf16 v[16:31], v[120:123], v[48:51], v[16:31]
	v_fma_f32 v48, v60, s37, -v70
	v_exp_f32_e32 v60, v48
	v_cvt_pk_bf16_f32 v48, v187, v188
	v_cvt_pk_bf16_f32 v49, v189, v186
	v_cvt_pk_bf16_f32 v50, v52, v53
	v_cvt_pk_bf16_f32 v51, v54, v55
	v_fma_f32 v52, v61, s37, -v70
	v_exp_f32_e32 v52, v52
	v_mfma_f32_32x32x16_bf16 v[32:47], v[116:119], v[48:51], v[32:47]
	v_fma_f32 v53, v62, s37, -v70
	v_exp_f32_e32 v53, v53
	v_add_f32_e32 v15, v60, v15
	v_mov_b32_e32 v186, v70
	v_mfma_f32_32x32x16_bf16 v[16:31], v[10:13], v[48:51], v[16:31]
	v_add_f32_e32 v10, v52, v15
	v_add_f32_e32 v10, v14, v10
	v_add_f32_e32 v15, v53, v10
	v_cvt_pk_bf16_f32 v10, v56, v57
	v_cvt_pk_bf16_f32 v11, v58, v59
	v_cvt_pk_bf16_f32 v12, v60, v52
	v_cvt_pk_bf16_f32 v13, v14, v53
	s_nop 1
	v_mfma_f32_32x32x16_bf16 v[32:47], v[6:9], v[10:13], v[32:47]
	ds_bpermute_b32 v6, v63, v15
	s_waitcnt lgkmcnt(0)
	v_add_f32_e32 v6, v15, v6
	v_fmac_f32_e32 v6, v165, v0
	v_mfma_f32_32x32x16_bf16 v[16:31], v[2:5], v[10:13], v[16:31]
	v_mov_b32_e32 v165, v6

; __global__ void __launch_bounds__(512, 2) mega_fwd(Params P) {
;   __shared__ __attribute__((aligned(16))) unsigned char smem[LDS_BYTES];
	.amdhsa_kernel _Z8mega_fwd6Params
		.amdhsa_group_segment_fixed_size 153616
		.amdhsa_private_segment_fixed_size 0
		.amdhsa_kernarg_size 456
		.amdhsa_user_sgpr_count 2
		.amdhsa_user_sgpr_dispatch_ptr 0
		.amdhsa_user_sgpr_queue_ptr 0
		.amdhsa_user_sgpr_kernarg_segment_ptr 1
		.amdhsa_user_sgpr_dispatch_id 0
		.amdhsa_user_sgpr_kernarg_preload_length 0
		.amdhsa_user_sgpr_kernarg_preload_offset 0
		.amdhsa_user_sgpr_private_segment_size 0
		.amdhsa_uses_dynamic_stack 0
		.amdhsa_enable_private_segment 0
		.amdhsa_system_sgpr_workgroup_id_x 1
		.amdhsa_system_sgpr_workgroup_id_y 0
		.amdhsa_system_sgpr_workgroup_id_z 0
		.amdhsa_system_sgpr_workgroup_info 0
		.amdhsa_system_vgpr_workitem_id 2
		.amdhsa_next_free_vgpr 256
		.amdhsa_next_free_sgpr 102
		.amdhsa_accum_offset 256
		.amdhsa_reserve_vcc 1
		.amdhsa_float_round_mode_32 0
		.amdhsa_float_round_mode_16_64 0
		.amdhsa_float_denorm_mode_32 3
		.amdhsa_float_denorm_mode_16_64 3
		.amdhsa_dx10_clamp 1
		.amdhsa_ieee_mode 1
		.amdhsa_fp16_overflow 0
		.amdhsa_tg_split 0
		.amdhsa_exception_fp_ieee_invalid_op 0
		.amdhsa_exception_fp_denorm_src 0
		.amdhsa_exception_fp_ieee_div_zero 0
		.amdhsa_exception_fp_ieee_overflow 0
		.amdhsa_exception_fp_ieee_underflow 0
		.amdhsa_exception_fp_ieee_inexact 0
		.amdhsa_exception_int_div_zero 0
	.end_amdhsa_kernel

; __global__ void __launch_bounds__(512, 2) mega_fwd(Params P) {
;   __shared__ __attribute__((aligned(16))) unsigned char smem[LDS_BYTES];
amdhsa.kernels:
  - .agpr_count:     0
    .args:
      - .offset:         0
        .size:           200
        .value_kind:     by_value
      - .offset:         200
        .size:           4
        .value_kind:     hidden_block_count_x
      - .offset:         204
        .size:           4
        .value_kind:     hidden_block_count_y
      - .offset:         208
        .size:           4
        .value_kind:     hidden_block_count_z
      - .offset:         212
        .size:           2
        .value_kind:     hidden_group_size_x
      - .offset:         214
        .size:           2
        .value_kind:     hidden_group_size_y
      - .offset:         216
        .size:           2
        .value_kind:     hidden_group_size_z
      - .offset:         218
        .size:           2
        .value_kind:     hidden_remainder_x
      - .offset:         220
        .size:           2
        .value_kind:     hidden_remainder_y
      - .offset:         222
        .size:           2
        .value_kind:     hidden_remainder_z
      - .offset:         240
        .size:           8
        .value_kind:     hidden_global_offset_x
      - .offset:         248
        .size:           8
        .value_kind:     hidden_global_offset_y
      - .offset:         256
        .size:           8
        .value_kind:     hidden_global_offset_z
      - .offset:         264
        .size:           2
        .value_kind:     hidden_grid_dims
      - .offset:         288
        .size:           8
        .value_kind:     hidden_multigrid_sync_arg
    .group_segment_fixed_size: 153616
    .kernarg_segment_align: 8
    .kernarg_segment_size: 456
    .language:       OpenCL C
    .language_version:
      - 2
      - 0
    .max_flat_workgroup_size: 512
    .name:           _Z8mega_fwd6Params
    .private_segment_fixed_size: 0
    .sgpr_count:     108
    .sgpr_spill_count: 130
    .symbol:         _Z8mega_fwd6Params.kd
    .uniform_work_group_size: 1
    .uses_dynamic_stack: false
    .vgpr_count:     256
    .vgpr_spill_count: 0
    .wavefront_size: 64
